# retention: group-norm partial sums via permlane16/32 swap transpose-reduce + unmasked LDS adds (no bpermute)
# speedup vs baseline: 1.0374x; 1.0071x over previous
; #define LAS __attribute__((address_space(3)))
; __device__ __forceinline__ float rms_r(float ss) { return __builtin_amdgcn_rsqf(ss * (1.0f / DM) + RMS_EPS); }
; __device__ __forceinline__ void ret_unit(LAS unsigned char* lds, bf16_t* QKV, float* gn, int b, int h, int vs, bool commit, const float* s00p, const float* ss3, bool skel = false) {
;     const int tid = threadIdx.x, lane = tid & 63, w = tid >> 6, fr = lane & 15, fq = lane >> 4;
;     LAS bf16_t* Kb = (LAS bf16_t*)lds;
;     LAS bf16_t* Ql = Kb + 2 * 64 * 264;
;     LAS bf16_t* Vb = Ql + 64 * 264;
;     LAS bf16_t* Pl = Vb + 2 * 64 * 136;
;     LAS float* st = (LAS float*)(Pl + 64 * 72);
;     const float l2g = __builtin_amdgcn_logf(1.0f - __builtin_amdgcn_exp2f(-5.0f - (float)h));
;     const float cd = __builtin_amdgcn_exp2f(64.f * l2g);
;     f32x4 state[16];
; #pragma unroll
;     for (int m = 0; m < 16; ++m) state[m] = (f32x4){0.f, 0.f, 0.f, 0.f};
;     const float s00 = s00p[b * 4 + h] * rms_r(ss3[(size_t)b * SEQ]) * rms_r(ss3[(size_t)b * SEQ]) * 0.0625f;
;     const int si = w & 3, ti0 = 2 * (w >> 2);
;     u32x4 pq[4], pkv[4], pv[2];
;     const int ls = tid & 63, lc8 = tid >> 6;
;     ...
;             if (fq == 0) { atomicAdd((float*)(st + (16 * n + fr) * 2), s1); atomicAdd((float*)(st + (16 * n + fr) * 2 + 1), s2); }
.LBB0_1130:
	v_readlane_b32 s52, v254, 6
	s_cmp_lt_i32 s52, 10
	s_cselect_b64 s[6:7], -1, 0
	s_add_u32 s0, s50, 0x180000
	s_addc_u32 s1, s51, 0
	s_and_b64 s[34:35], s[6:7], s[4:5]
	s_xor_b64 s[4:5], s[34:35], -1
	s_cmpk_gt_i32 s2, 0xff
	s_cselect_b64 s[6:7], -1, 0
	s_or_b64 s[4:5], s[4:5], s[6:7]
	v_readlane_b32 s53, v254, 7
	v_readlane_b32 s54, v254, 8
	v_readlane_b32 s55, v254, 9
	s_and_b64 vcc, exec, s[4:5]
	s_cbranch_vccnz .LBB0_1160
	v_and_b32_e32 v128, 63, v176
	s_add_u32 s33, s50, 0x60000
	v_mul_u32_u24_e32 v2, 0x108, v128
	s_addc_u32 s70, s51, 0
	v_bfe_u32 v3, v176, 6, 2
	s_add_i32 s38, 0, 0x10800
	v_lshlrev_b32_e32 v4, 1, v2
	v_lshlrev_b32_e32 v2, 4, v224
	v_and_b32_e32 v130, 15, v176
	v_add3_u32 v129, s38, v4, v2
	v_add3_u32 v131, 0, v4, v2
	v_mul_u32_u24_e32 v4, 0x110, v128
	s_add_i32 s8, 0, 0x18c00
	v_lshlrev_b32_e32 v6, 4, v3
	s_waitcnt lgkmcnt(0)
	v_bfe_u32 v1, v176, 4, 2
	v_add3_u32 v135, s8, v4, v2
	v_or_b32_e32 v4, v6, v130
	s_waitcnt vmcnt(0)
	v_lshlrev_b32_e32 v10, 5, v224
	v_and_b32_e32 v12, 1, v176
	v_mul_u32_u24_e32 v163, 0x210, v4
	v_lshlrev_b32_e32 v4, 2, v1
	v_add_u32_e32 v11, s8, v10
	v_lshlrev_b32_e32 v132, 2, v12
	v_lshrrev_b32_e32 v12, 3, v176
	s_movk_i32 s8, 0x60
	v_lshlrev_b32_e32 v5, 2, v176
	s_add_i32 s71, 0, 0x23800
	v_lshlrev_b32_e32 v164, 3, v1
	v_and_b32_e32 v7, 48, v176
	v_or_b32_e32 v1, v6, v4
	v_and_or_b32 v12, v12, s8, v130
	v_add_u32_e32 v162, s71, v5
	s_movk_i32 s42, 0x210
	v_add_u32_e32 v8, s38, v7
	s_add_i32 s9, 0, 0x21400
	v_lshlrev_b32_e32 v6, 5, v3
	v_and_b32_e32 v5, 12, v5
	v_or_b32_e32 v14, 16, v12
	v_or_b32_e32 v15, 2, v1
	v_or_b32_e32 v16, 3, v1
	v_add3_u32 v6, s9, v6, v164
	v_lshlrev_b32_e32 v165, 1, v5
	v_add_u32_e32 v5, s9, v7
	v_mul_u32_u24_e32 v13, 0x210, v12
	v_mad_u32_u24 v167, v12, s42, v8
	v_cmp_lt_u32_e64 s[8:9], v12, v1
	v_cmp_gt_u32_e64 s[10:11], v12, v1
	v_cmp_lt_u32_e64 s[12:13], v12, v15
	v_cmp_lt_u32_e64 s[14:15], v12, v16
	v_or_b32_e32 v169, v12, v3
	v_mul_u32_u24_e32 v3, 0x90, v12
	v_cmp_lt_u32_e64 s[16:17], v14, v1
	v_cmp_gt_u32_e64 s[18:19], v14, v1
	v_cmp_lt_u32_e64 s[20:21], v14, v15
	v_cmp_lt_u32_e64 s[22:23], v14, v16
	v_mov_b32_e32 v12, 0x2100
	v_mov_b32_e32 v14, 0x4200
	v_mov_b32_e32 v15, 0x6300
	v_mul_u32_u24_e32 v1, 0x210, v130
	v_mad_u32_u24 v12, v130, s42, v12
	v_mad_u32_u24 v14, v130, s42, v14
	v_mad_u32_u24 v15, v130, s42, v15
	v_add3_u32 v170, s38, v1, v164
	v_add3_u32 v171, s38, v12, v164
	v_add3_u32 v172, s38, v14, v164
	v_add3_u32 v173, s38, v15, v164
	s_add_i32 s38, 0, 0x10880
	v_add3_u32 v174, s38, v1, v164
	v_add3_u32 v175, s38, v12, v164
	v_add3_u32 v177, s38, v14, v164
	v_add3_u32 v178, s38, v15, v164
	s_add_i32 s38, 0, 0x108c0
	v_add3_u32 v179, s38, v1, v164
	v_add3_u32 v180, s38, v12, v164
	v_add3_u32 v181, s38, v14, v164
	v_add3_u32 v182, s38, v15, v164
	s_add_i32 s38, 0, 0x10900
	v_add3_u32 v183, s38, v1, v164
	v_add3_u32 v184, s38, v12, v164
	v_add3_u32 v185, s38, v14, v164
	v_add3_u32 v186, s38, v15, v164
	s_add_i32 s38, 0, 0x10940
	v_bfe_u32 v9, v176, 2, 2
	v_add3_u32 v187, s38, v1, v164
	v_add3_u32 v188, s38, v12, v164
	v_add3_u32 v189, s38, v14, v164
	v_add3_u32 v190, s38, v15, v164
	s_add_i32 s38, 0, 0x10980
	v_lshlrev_b32_e32 v0, 3, v224
	v_or_b32_e32 v9, v164, v9
	v_lshrrev_b32_e32 v134, 1, v176
	v_add3_u32 v191, s38, v1, v164
	v_add3_u32 v192, s38, v12, v164
	v_add3_u32 v193, s38, v14, v164
	v_add3_u32 v194, s38, v15, v164
	s_add_i32 s38, 0, 0x109c0
	v_add3_u32 v201, 0, v163, v7
	v_lshlrev_b32_e32 v7, 13, v130
	v_mov_b32_e32 v133, 0
	s_movk_i32 s4, 0x80
	v_add3_u32 v195, s38, v1, v164
	v_add3_u32 v196, s38, v12, v164
	v_add3_u32 v197, s38, v14, v164
	v_add3_u32 v198, s38, v15, v164
	v_mul_u32_u24_e32 v1, 0x90, v130
	v_mul_u32_u24_e32 v12, 0x110, v9
	v_lshl_or_b32 v138, v128, 13, v2
	v_or3_b32 v142, v7, v10, v164
	v_lshlrev_b32_e32 v7, 5, v134
	s_mov_b32 s38, 0x180000
	v_lshlrev_b32_e32 v146, 1, v0
	v_mbcnt_lo_u32_b32 v0, -1, 0
	s_mov_b32 s39, 0
	v_cmp_gt_u32_e64 s[4:5], s4, v176
	v_cmp_gt_u32_e64 s[6:7], 16, v128
	v_lshlrev_b32_e32 v166, 3, v130
	v_lshl_add_u64 v[136:137], s[0:1], 0, v[132:133]
	v_add_u32_e32 v168, 0x2100, v167
	v_mul_u32_u24_e32 v199, 0x210, v9
	v_add3_u32 v200, v11, v165, v12
	v_mov_b32_e32 v139, v133
	v_or_b32_e32 v140, 0xe300800, v138
	v_mov_b32_e32 v141, v133
	v_mov_b32_e32 v143, v133
	s_lshl_b32 s73, s2, 4
	s_lshl_b32 s74, s54, 4
	v_or3_b32 v144, v7, v132, s38
	v_mov_b32_e32 v145, v133
	s_mov_b64 s[42:43], 0x41000
	s_movk_i32 s75, 0x1000
	s_mov_b64 s[52:53], 0x80000
	s_mov_b32 s76, 0x80000
	s_mov_b64 s[54:55], 0x81000
	v_mbcnt_hi_u32_b32 v202, -1, v0
	s_mov_b64 s[56:57], 0x800
	v_lshlrev_b32_e32 v132, 1, v2
	v_lshlrev_b32_e32 v148, 1, v4
	v_add_u32_e32 v203, v8, v13
	v_add_u32_e32 v204, v6, v3
	v_add_u32_e32 v205, v5, v1
	s_mov_b32 s77, s2
	s_mov_b32 s78, s2
	v_lshrrev_b32_e32 v129, 5, v176
	v_mul_u32_u24_e32 v129, 0x210, v129
	v_and_b32_e32 v255, 31, v176
	v_lshl_add_u32 v129, v255, 4, v129
	v_mov_b32_e32 v131, v129
	v_add_u32_e32 v129, 0x10800, v129
	v_lshrrev_b32_e32 v135, 4, v176
	v_mul_u32_u24_e32 v135, 0x110, v135
	v_lshl_add_u32 v135, v130, 4, v135
	v_add_u32_e32 v135, 0x18c00, v135
	v_lshrrev_b32_e32 v146, 5, v176
	v_lshlrev_b32_e32 v255, 4, v255
	v_lshl_or_b32 v146, v146, 13, v255
	v_or_b32_e32 v140, 0xe300800, v146
	v_lshrrev_b32_e32 v138, 4, v176
	v_lshlrev_b32_e32 v255, 4, v130
	v_lshl_or_b32 v138, v138, 13, v255
	s_mov_b64 s[98:99], 0x20000
	s_mov_b64 s[100:101], 0x40000
	v_and_b32_e32 v255, 16, v176
	v_lshlrev_b32_e32 v255, 4, v255
	v_and_b32_e32 v0, 32, v176
	v_lshl_or_b32 v255, v0, 2, v255
	v_lshl_or_b32 v255, v130, 3, v255
	v_add_u32_e32 v255, 0x23800, v255
	s_branch .LBB0_1133

; #define LAS __attribute__((address_space(3)))
; #define SB0 __builtin_amdgcn_sched_barrier(0)
; #define SB0 __builtin_amdgcn_sched_barrier(0)
; #define RD_LOAD(m_) do { _Pragma("unroll") for (int ks = 0; ks < 2; ++ks) TR_FRAG(kf[(m_) % 3][ks], Kl, 264, 16 * (m_), ks); } while (0)
; __device__ __forceinline__ void ret_unit(LAS unsigned char* lds, bf16_t* QKV, float* gn, int b, int h, int vs, bool commit, const float* s00p, const float* ss3, bool skel = false) {
;     ...
;         if (!skel) {
;         bf16x8 vfrag[2];
;         { bf16x8 pf[2][4];
; #pragma unroll
;           for (int ks = 0; ks < 2; ++ks) { TR_FRAG(vfrag[ks], Vl, 136, 16 * w, ks);
; #pragma unroll
;               for (int n = 0; n < 4; ++n) pf[ks][n] = *(const LAS bf16x8*)(Pl + (16 * n + fr) * 72 + 32 * ks + 8 * fq); }
;           bf16x8 kf[3][2];
;     ...
;           RD_LOAD(0); RD_LOAD(1); SB0;
; #pragma unroll
;           for (int ks = 0; ks < 2; ++ks)
; #pragma unroll
;               for (int n = 0; n < 4; ++n) oacc[n] = __builtin_amdgcn_mfma_f32_16x16x32_bf16(vfrag[ks], pf[ks][n], oacc[n], 0, 0, 0);
;           SB0;
; #pragma unroll
;           for (int m = 0; m < 16; ++m) { if (m + 2 < 16) RD_LOAD(m + 2);
;               state[m] = state[m] * cd; SB0;
; #pragma unroll
;               for (int ks = 0; ks < 2; ++ks) state[m] = __builtin_amdgcn_mfma_f32_16x16x32_bf16(kf[m % 3][ks], vfrag[ks], state[m], 0, 0, 0);
;               SB0; }
;     ...
;         }
.LBB0_1139:
	s_mulk_i32 s65, 0x4400
	v_mov_b32_e32 v151, v150
	v_add_u32_e32 v122, s65, v200
	v_pk_mul_f32 v[126:127], v[150:151], v[118:119]
	v_pk_mul_f32 v[124:125], v[152:153], v[116:117]
	ds_read_b64_tr_b16 v[116:117], v122
	ds_read_b64_tr_b16 v[118:119], v122 offset:1088
	ds_read_b128 v[206:209], v205
	ds_read_b128 v[210:213], v205 offset:2304
	ds_read_b128 v[214:217], v205 offset:4608
	ds_read_b128 v[218:221], v205 offset:6912
	ds_read_b64_tr_b16 v[120:121], v122 offset:8704
	ds_read_b64_tr_b16 v[122:123], v122 offset:9792
	ds_read_b128 v[222:225], v205 offset:64
	ds_read_b128 v[226:229], v205 offset:2368
	ds_read_b128 v[230:233], v205 offset:4672
	ds_read_b128 v[234:237], v205 offset:6976
	v_add3_u32 v149, s64, v165, v199
	v_add3_u32 v252, s64, v199, v165
	ds_read_b64_tr_b16 v[238:239], v149
	ds_read_b64_tr_b16 v[240:241], v149 offset:2112
	ds_read_b64_tr_b16 v[242:243], v149 offset:16896
	ds_read_b64_tr_b16 v[244:245], v149 offset:19008
	ds_read_b64_tr_b16 v[246:247], v252 offset:32
	ds_read_b64_tr_b16 v[248:249], v252 offset:2144
	ds_read_b64_tr_b16 v[250:251], v252 offset:16928
	ds_read_b64_tr_b16 v[252:253], v252 offset:19040
	v_pk_mul_f32 v[114:115], v[150:151], v[114:115]
	v_pk_mul_f32 v[112:113], v[152:153], v[112:113]
	v_pk_mul_f32 v[110:111], v[150:151], v[110:111]
	v_pk_mul_f32 v[108:109], v[152:153], v[108:109]
	v_pk_mul_f32 v[106:107], v[150:151], v[106:107]
	v_pk_mul_f32 v[104:105], v[152:153], v[104:105]
	s_waitcnt lgkmcnt(14)
	v_mfma_f32_16x16x32_bf16 v[124:127], v[116:119], v[206:209], v[124:127]
	v_mfma_f32_16x16x32_bf16 v[112:115], v[116:119], v[210:213], v[112:115]
	v_mfma_f32_16x16x32_bf16 v[108:111], v[116:119], v[214:217], v[108:111]
	v_mfma_f32_16x16x32_bf16 v[104:107], v[116:119], v[218:221], v[104:107]
	s_waitcnt lgkmcnt(11)
	v_mfma_f32_16x16x32_bf16 v[124:127], v[120:123], v[222:225], v[124:127]
	s_waitcnt lgkmcnt(10)
	v_mfma_f32_16x16x32_bf16 v[112:115], v[120:123], v[226:229], v[112:115]
	s_waitcnt lgkmcnt(9)
	v_mfma_f32_16x16x32_bf16 v[108:111], v[120:123], v[230:233], v[108:111]
	s_waitcnt lgkmcnt(8)
	v_mfma_f32_16x16x32_bf16 v[104:107], v[120:123], v[234:237], v[104:107]
	ds_read_b64_tr_b16 v[206:207], v149 offset:64
	ds_read_b64_tr_b16 v[208:209], v149 offset:2176
	ds_read_b64_tr_b16 v[210:211], v149 offset:16960
	ds_read_b64_tr_b16 v[212:213], v149 offset:19072
	v_pk_mul_f32 v[62:63], v[150:151], v[62:63]
	v_pk_mul_f32 v[60:61], v[152:153], v[60:61]
	s_waitcnt lgkmcnt(10)
	s_nop 0
	v_mfma_f32_16x16x32_bf16 v[60:63], v[238:241], v[116:119], v[60:63]
	s_waitcnt lgkmcnt(8)
	v_mfma_f32_16x16x32_bf16 v[60:63], v[242:245], v[120:123], v[60:63]
	ds_read_b64_tr_b16 v[214:215], v149 offset:96
	ds_read_b64_tr_b16 v[216:217], v149 offset:2208
	ds_read_b64_tr_b16 v[218:219], v149 offset:16992
	ds_read_b64_tr_b16 v[220:221], v149 offset:19104
	v_pk_mul_f32 v[58:59], v[150:151], v[58:59]
	v_pk_mul_f32 v[56:57], v[152:153], v[56:57]
	s_waitcnt lgkmcnt(10)
	s_nop 0
	v_mfma_f32_16x16x32_bf16 v[56:59], v[246:249], v[116:119], v[56:59]
	s_waitcnt lgkmcnt(8)
	v_mfma_f32_16x16x32_bf16 v[56:59], v[250:253], v[120:123], v[56:59]
	ds_read_b64_tr_b16 v[222:223], v149 offset:128
	ds_read_b64_tr_b16 v[224:225], v149 offset:2240
	ds_read_b64_tr_b16 v[226:227], v149 offset:17024
	ds_read_b64_tr_b16 v[228:229], v149 offset:19136
	v_pk_mul_f32 v[54:55], v[150:151], v[54:55]
	v_pk_mul_f32 v[52:53], v[152:153], v[52:53]
	s_waitcnt lgkmcnt(10)
	s_nop 0
	v_mfma_f32_16x16x32_bf16 v[52:55], v[206:209], v[116:119], v[52:55]
	s_waitcnt lgkmcnt(8)
	v_mfma_f32_16x16x32_bf16 v[52:55], v[210:213], v[120:123], v[52:55]
	ds_read_b64_tr_b16 v[206:207], v149 offset:160
	ds_read_b64_tr_b16 v[208:209], v149 offset:2272
	ds_read_b64_tr_b16 v[210:211], v149 offset:17056
	ds_read_b64_tr_b16 v[212:213], v149 offset:19168
	v_pk_mul_f32 v[50:51], v[150:151], v[50:51]
	v_pk_mul_f32 v[48:49], v[152:153], v[48:49]
	s_waitcnt lgkmcnt(10)
	s_nop 0
	v_mfma_f32_16x16x32_bf16 v[48:51], v[214:217], v[116:119], v[48:51]
	s_waitcnt lgkmcnt(8)
	v_mfma_f32_16x16x32_bf16 v[48:51], v[218:221], v[120:123], v[48:51]
	ds_read_b64_tr_b16 v[214:215], v149 offset:192
	ds_read_b64_tr_b16 v[216:217], v149 offset:2304
	ds_read_b64_tr_b16 v[218:219], v149 offset:17088
	ds_read_b64_tr_b16 v[220:221], v149 offset:19200
	v_pk_mul_f32 v[46:47], v[150:151], v[46:47]
	v_pk_mul_f32 v[44:45], v[152:153], v[44:45]
	s_waitcnt lgkmcnt(10)
	s_nop 0
	v_mfma_f32_16x16x32_bf16 v[44:47], v[222:225], v[116:119], v[44:47]
	s_waitcnt lgkmcnt(8)
	v_mfma_f32_16x16x32_bf16 v[44:47], v[226:229], v[120:123], v[44:47]
	ds_read_b64_tr_b16 v[222:223], v149 offset:224
	ds_read_b64_tr_b16 v[224:225], v149 offset:2336
	ds_read_b64_tr_b16 v[226:227], v149 offset:17120
	ds_read_b64_tr_b16 v[228:229], v149 offset:19232
	v_pk_mul_f32 v[42:43], v[150:151], v[42:43]
	v_pk_mul_f32 v[40:41], v[152:153], v[40:41]
	s_waitcnt lgkmcnt(10)
	s_nop 0
	v_mfma_f32_16x16x32_bf16 v[40:43], v[206:209], v[116:119], v[40:43]
	s_waitcnt lgkmcnt(8)
	v_mfma_f32_16x16x32_bf16 v[40:43], v[210:213], v[120:123], v[40:43]
	ds_read_b64_tr_b16 v[206:207], v149 offset:256
	ds_read_b64_tr_b16 v[208:209], v149 offset:2368
	ds_read_b64_tr_b16 v[210:211], v149 offset:17152
	ds_read_b64_tr_b16 v[212:213], v149 offset:19264
	v_pk_mul_f32 v[38:39], v[150:151], v[38:39]
	v_pk_mul_f32 v[36:37], v[152:153], v[36:37]
	s_waitcnt lgkmcnt(10)
	s_nop 0
	v_mfma_f32_16x16x32_bf16 v[36:39], v[214:217], v[116:119], v[36:39]
	s_waitcnt lgkmcnt(8)
	v_mfma_f32_16x16x32_bf16 v[36:39], v[218:221], v[120:123], v[36:39]
	ds_read_b64_tr_b16 v[214:215], v149 offset:288
	ds_read_b64_tr_b16 v[216:217], v149 offset:2400
	ds_read_b64_tr_b16 v[218:219], v149 offset:17184
	ds_read_b64_tr_b16 v[220:221], v149 offset:19296
	v_pk_mul_f32 v[34:35], v[150:151], v[34:35]
	v_pk_mul_f32 v[32:33], v[152:153], v[32:33]
	s_waitcnt lgkmcnt(10)
; __device__ __forceinline__ u32x2 pack4(f32x4 v) { return (u32x2){pk2(v[0], v[1]), pk2(v[2], v[3])}; }
; #define LDS_BAR() do { asm volatile("s_waitcnt lgkmcnt(0)" ::: "memory"); __builtin_amdgcn_s_barrier(); asm volatile("" ::: "memory"); } while (0)
; #define SB0 __builtin_amdgcn_sched_barrier(0)
; #define SB0 __builtin_amdgcn_sched_barrier(0)
; #define RD_LOAD(m_) do { _Pragma("unroll") for (int ks = 0; ks < 2; ++ks) TR_FRAG(kf[(m_) % 3][ks], Kl, 264, 16 * (m_), ks); } while (0)
; __device__ __forceinline__ void ret_unit(LAS unsigned char* lds, bf16_t* QKV, float* gn, int b, int h, int vs, bool commit, const float* s00p, const float* ss3, bool skel = false) {
;     ...
;           for (int m = 0; m < 16; ++m) { if (m + 2 < 16) RD_LOAD(m + 2);
;               state[m] = state[m] * cd; SB0;
; #pragma unroll
;               for (int ks = 0; ks < 2; ++ks) state[m] = __builtin_amdgcn_mfma_f32_16x16x32_bf16(kf[m % 3][ks], vfrag[ks], state[m], 0, 0, 0);
;               SB0; }
;     ...
;         }
;         }
;     ...
; #pragma unroll
;         for (int n = 0; n < 4; ++n) { const f32x4 o = oacc[n];
;             float s1 = (o[0] + o[1]) + (o[2] + o[3]), s2 = (o[0] * o[0] + o[1] * o[1]) + (o[2] * o[2] + o[3] * o[3]);
;             s1 += __shfl_xor(s1, 16); s1 += __shfl_xor(s1, 32); s2 += __shfl_xor(s2, 16); s2 += __shfl_xor(s2, 32);
;             if (fq == 0) { atomicAdd((float*)(st + (16 * n + fr) * 2), s1); atomicAdd((float*)(st + (16 * n + fr) * 2 + 1), s2); }
;             if (commit) *(u32x2*)(QKV + (trow0 + 16 * n + fr) * RET_QKV + 2048 + 512 * h + 128 * vs + 16 * w + 4 * fq) = pack4(o); }
;         LDS_BAR();
;         if (tid < 128) { if (commit) atomicAdd(gn + ((trow0 + (tid >> 1)) * 4 + h) * 2 + (tid & 1), st[tid]); st[tid] = 0.f; }
	s_nop 0
	v_mfma_f32_16x16x32_bf16 v[32:35], v[222:225], v[116:119], v[32:35]
	s_waitcnt lgkmcnt(8)
	v_mfma_f32_16x16x32_bf16 v[32:35], v[226:229], v[120:123], v[32:35]
	ds_read_b64_tr_b16 v[222:223], v149 offset:320
	ds_read_b64_tr_b16 v[224:225], v149 offset:2432
	ds_read_b64_tr_b16 v[226:227], v149 offset:17216
	ds_read_b64_tr_b16 v[228:229], v149 offset:19328
	v_pk_mul_f32 v[30:31], v[150:151], v[30:31]
	v_pk_mul_f32 v[28:29], v[152:153], v[28:29]
	s_waitcnt lgkmcnt(10)
	s_nop 0
	v_mfma_f32_16x16x32_bf16 v[28:31], v[206:209], v[116:119], v[28:31]
	s_waitcnt lgkmcnt(8)
	v_mfma_f32_16x16x32_bf16 v[28:31], v[210:213], v[120:123], v[28:31]
	ds_read_b64_tr_b16 v[206:207], v149 offset:352
	ds_read_b64_tr_b16 v[208:209], v149 offset:2464
	ds_read_b64_tr_b16 v[210:211], v149 offset:17248
	ds_read_b64_tr_b16 v[212:213], v149 offset:19360
	v_pk_mul_f32 v[26:27], v[150:151], v[26:27]
	v_pk_mul_f32 v[24:25], v[152:153], v[24:25]
	s_waitcnt lgkmcnt(10)
	s_nop 0
	v_mfma_f32_16x16x32_bf16 v[24:27], v[214:217], v[116:119], v[24:27]
	s_waitcnt lgkmcnt(8)
	v_mfma_f32_16x16x32_bf16 v[24:27], v[218:221], v[120:123], v[24:27]
	ds_read_b64_tr_b16 v[214:215], v149 offset:384
	ds_read_b64_tr_b16 v[216:217], v149 offset:2496
	ds_read_b64_tr_b16 v[218:219], v149 offset:17280
	ds_read_b64_tr_b16 v[220:221], v149 offset:19392
	v_pk_mul_f32 v[22:23], v[150:151], v[22:23]
	v_pk_mul_f32 v[20:21], v[152:153], v[20:21]
	s_waitcnt lgkmcnt(10)
	s_nop 0
	v_mfma_f32_16x16x32_bf16 v[20:23], v[222:225], v[116:119], v[20:23]
	s_waitcnt lgkmcnt(8)
	v_mfma_f32_16x16x32_bf16 v[20:23], v[226:229], v[120:123], v[20:23]
	ds_read_b64_tr_b16 v[222:223], v149 offset:416
	ds_read_b64_tr_b16 v[224:225], v149 offset:2528
	ds_read_b64_tr_b16 v[226:227], v149 offset:17312
	ds_read_b64_tr_b16 v[228:229], v149 offset:19424
	v_pk_mul_f32 v[18:19], v[150:151], v[18:19]
	v_pk_mul_f32 v[16:17], v[152:153], v[16:17]
	s_waitcnt lgkmcnt(10)
	s_nop 0
	v_mfma_f32_16x16x32_bf16 v[16:19], v[206:209], v[116:119], v[16:19]
	s_waitcnt lgkmcnt(8)
	v_mfma_f32_16x16x32_bf16 v[16:19], v[210:213], v[120:123], v[16:19]
	ds_read_b64_tr_b16 v[206:207], v149 offset:448
	ds_read_b64_tr_b16 v[208:209], v149 offset:2560
	ds_read_b64_tr_b16 v[210:211], v149 offset:17344
	ds_read_b64_tr_b16 v[212:213], v149 offset:19456
	v_pk_mul_f32 v[14:15], v[150:151], v[14:15]
	v_pk_mul_f32 v[12:13], v[152:153], v[12:13]
	s_waitcnt lgkmcnt(10)
	s_nop 0
	v_mfma_f32_16x16x32_bf16 v[12:15], v[214:217], v[116:119], v[12:15]
	s_waitcnt lgkmcnt(8)
	v_mfma_f32_16x16x32_bf16 v[12:15], v[218:221], v[120:123], v[12:15]
	ds_read_b64_tr_b16 v[214:215], v149 offset:480
	ds_read_b64_tr_b16 v[216:217], v149 offset:2592
	ds_read_b64_tr_b16 v[218:219], v149 offset:17376
	ds_read_b64_tr_b16 v[220:221], v149 offset:19488
	v_pk_mul_f32 v[10:11], v[150:151], v[10:11]
	v_pk_mul_f32 v[8:9], v[152:153], v[8:9]
	s_waitcnt lgkmcnt(10)
	s_nop 0
	v_mfma_f32_16x16x32_bf16 v[8:11], v[222:225], v[116:119], v[8:11]
	s_waitcnt lgkmcnt(8)
	v_mfma_f32_16x16x32_bf16 v[8:11], v[226:229], v[120:123], v[8:11]
	v_mul_f32_e64 v6, v150, v6
	v_mul_f32_e64 v7, v151, v7
	v_pk_mul_f32 v[4:5], v[152:153], v[4:5]
	s_waitcnt lgkmcnt(6)
	s_nop 0
	v_mfma_f32_16x16x32_bf16 v[4:7], v[206:209], v[116:119], v[4:7]
	s_waitcnt lgkmcnt(4)
	v_mfma_f32_16x16x32_bf16 v[4:7], v[210:213], v[120:123], v[4:7]
	v_mul_f32_e64 v2, v150, v2
	v_mul_f32_e64 v3, v151, v3
	v_pk_mul_f32 v[0:1], v[152:153], v[0:1]
	s_waitcnt lgkmcnt(2)
	s_nop 0
	v_mfma_f32_16x16x32_bf16 v[0:3], v[214:217], v[116:119], v[0:3]
	s_waitcnt lgkmcnt(0)
	v_mfma_f32_16x16x32_bf16 v[0:3], v[218:221], v[120:123], v[0:3]
	v_and_b32_e32 v117, 64, v202
	v_xor_b32_e32 v116, 16, v202
	v_add_u32_e32 v117, 64, v117
	v_cmp_lt_i32_e32 vcc, v116, v117
	v_add_f32_e32 v222, v124, v125
	v_add_f32_e32 v230, v126, v127
	v_cndmask_b32_e32 v116, v202, v116, vcc
	v_lshlrev_b32_e32 v118, 2, v116
	v_xor_b32_e32 v116, 32, v202
	v_cmp_lt_i32_e32 vcc, v116, v117
	v_mul_f32_e32 v226, v124, v124
	v_mul_f32_e32 v231, v126, v126
	v_cndmask_b32_e32 v116, v202, v116, vcc
	v_lshlrev_b32_e32 v119, 2, v116
	v_add_f32_e32 v223, v112, v113
	v_add_f32_e32 v232, v114, v115
	v_fmac_f32_e32 v226, v125, v125
	v_fmac_f32_e32 v231, v127, v127
	v_mul_f32_e32 v227, v112, v112
	v_mul_f32_e32 v233, v114, v114
	v_add_f32_e32 v222, v222, v230
	v_add_f32_e32 v226, v226, v231
	v_fmac_f32_e32 v227, v113, v113
	v_fmac_f32_e32 v233, v115, v115
	v_add_f32_e32 v223, v223, v232
	v_add_f32_e32 v224, v108, v109
	v_add_f32_e32 v230, v110, v111
	v_add_f32_e32 v227, v227, v233
	v_mul_f32_e32 v228, v108, v108
	v_mul_f32_e32 v231, v110, v110
	v_add_f32_e32 v225, v104, v105
	v_add_f32_e32 v232, v106, v107
	v_fmac_f32_e32 v228, v109, v109
	v_fmac_f32_e32 v231, v111, v111
	v_mul_f32_e32 v229, v104, v104
	v_mul_f32_e32 v233, v106, v106
	v_add_f32_e32 v224, v224, v230
	v_add_f32_e32 v228, v228, v231
	v_fmac_f32_e32 v229, v105, v105
	v_fmac_f32_e32 v233, v107, v107
	v_add_f32_e32 v225, v225, v232
	v_add_f32_e32 v229, v229, v233
	v_lshl_add_u64 v[116:117], s[50:51], 0, v[156:157]
	s_nop 1
	v_permlane16_swap_b32_e32 v222, v224
	v_permlane16_swap_b32_e32 v226, v228
	v_permlane16_swap_b32_e32 v223, v225
	v_permlane16_swap_b32_e32 v227, v229
	v_add_f32_e32 v222, v222, v224
	v_add_f32_e32 v226, v226, v228
	v_add_f32_e32 v223, v223, v225
	v_add_f32_e32 v227, v227, v229
	v_cvt_pk_bf16_f32 v124, v124, v125
	v_cvt_pk_bf16_f32 v125, v126, v127
	v_permlane32_swap_b32_e32 v222, v223
	v_permlane32_swap_b32_e32 v226, v227
	v_add_co_u32_e32 v126, vcc, 0xe201000, v116
	v_add_f32_e32 v222, v222, v223
	v_add_f32_e32 v226, v226, v227
	v_addc_co_u32_e32 v127, vcc, 0, v117, vcc
	ds_add_f32 v255, v222
	ds_add_f32 v255, v226 offset:4
	global_store_dwordx2 v[126:127], v[124:125], off
	v_cvt_pk_bf16_f32 v120, v112, v113
	v_cvt_pk_bf16_f32 v121, v114, v115
	v_add_co_u32_e32 v122, vcc, 0xe221000, v116
	s_nop 1
	v_addc_co_u32_e32 v123, vcc, 0, v117, vcc
	global_store_dwordx2 v[122:123], v[120:121], off
	v_cvt_pk_bf16_f32 v112, v108, v109
	v_cvt_pk_bf16_f32 v113, v110, v111
	v_add_co_u32_e32 v114, vcc, 0xe241000, v116
	s_nop 1
	v_addc_co_u32_e32 v115, vcc, 0, v117, vcc
	global_store_dwordx2 v[114:115], v[112:113], off
	v_cvt_pk_bf16_f32 v104, v104, v105
	v_cvt_pk_bf16_f32 v105, v106, v107
	v_add_co_u32_e32 v106, vcc, 0xe261000, v116
	s_nop 1
	v_addc_co_u32_e32 v107, vcc, 0, v117, vcc
	global_store_dwordx2 v[106:107], v[104:105], off
	s_waitcnt lgkmcnt(0)
	s_barrier
	s_and_saveexec_b64 s[64:65], s[4:5]
	s_cbranch_execz .LBB0_1136
	ds_read_b32 v106, v162
	v_lshl_add_u64 v[104:105], s[50:51], 0, v[158:159]
	s_waitcnt lgkmcnt(0)
	global_atomic_add_f32 v[104:105], v106, off
	ds_write_b32 v162, v133
	s_branch .LBB0_1136
